# diff_attn unit finalisation: 8 dwordx2 stores -> 4 dwordx4 via permlane32+permlane16 swap pairing of adjacent feature blocks
# speedup vs baseline: 1.0240x; 1.0080x over previous
.Ldf_nodrain:
	s_waitcnt vmcnt(0)
	s_and_saveexec_b64 s[6:7], s[0:1]
	s_xor_b64 s[0:1], exec, s[6:7]
	s_cbranch_execz .LBB0_1582
	v_div_scale_f32 v0, s[6:7], v88, v88, 1.0
	v_rcp_f32_e32 v2, v0
	v_div_scale_f32 v3, vcc, 1.0, v88, 1.0
	v_readlane_b32 s36, v255, 2
	v_fma_f32 v4, -v0, v2, 1.0
	v_fmac_f32_e32 v2, v4, v2
	v_mul_f32_e32 v4, v3, v2
	v_fma_f32 v5, -v0, v4, v3
	v_fmac_f32_e32 v4, v5, v2
	v_fma_f32 v0, -v0, v4, v3
	v_div_scale_f32 v3, s[6:7], v76, v76, v141
	v_rcp_f32_e32 v5, v3
	v_div_fmas_f32 v0, v0, v2, v4
	v_div_fixup_f32 v0, v0, v88, 1.0
	v_readlane_b32 s50, v255, 16
	v_fma_f32 v2, -v3, v5, 1.0
	v_fmac_f32_e32 v5, v2, v5
	v_div_scale_f32 v2, vcc, v141, v76, v141
	v_mul_f32_e32 v4, v2, v5
	v_fma_f32 v6, -v3, v4, v2
	v_fmac_f32_e32 v4, v6, v5
	v_fma_f32 v2, -v3, v4, v2
	v_div_fmas_f32 v2, v2, v5, v4
	v_div_fixup_f32 v6, v2, v76, v141
	v_pk_mul_f32 v[2:3], v[80:81], v[6:7] op_sel_hi:[1,0]
	v_readlane_b32 s51, v255, 17
	v_pk_fma_f32 v[8:9], v[84:85], v[0:1], v[2:3] op_sel_hi:[1,0,1] neg_lo:[0,0,1] neg_hi:[0,0,1]
	v_pk_mul_f32 v[2:3], v[82:83], v[6:7] op_sel_hi:[1,0]
	v_pk_mul_f32 v[66:67], v[66:67], v[6:7] op_sel_hi:[1,0]
	v_pk_fma_f32 v[12:13], v[86:87], v[0:1], v[2:3] op_sel_hi:[1,0,1] neg_lo:[0,0,1] neg_hi:[0,0,1]
	v_pk_mul_f32 v[2:3], v[74:75], v[6:7] op_sel_hi:[1,0]
	v_pk_mul_f32 v[64:65], v[64:65], v[6:7] op_sel_hi:[1,0]
	v_pk_fma_f32 v[16:17], v[70:71], v[0:1], v[2:3] op_sel_hi:[1,0,1] neg_lo:[0,0,1] neg_hi:[0,0,1]
	global_load_dwordx4 v[182:185], v108, s[50:51]
	global_load_dwordx4 v[186:189], v108, s[50:51] offset:64
	global_load_dwordx4 v[190:193], v108, s[50:51] offset:128
	global_load_dwordx4 v[194:197], v108, s[50:51] offset:192
	global_load_dwordx4 v[198:201], v108, s[50:51] offset:256
	global_load_dwordx4 v[202:205], v108, s[50:51] offset:320
	global_load_dwordx4 v[206:209], v108, s[50:51] offset:384
	global_load_dwordx4 v[210:213], v108, s[50:51] offset:448
	v_pk_mul_f32 v[70:71], v[72:73], v[6:7] op_sel_hi:[1,0]
	v_pk_mul_f32 v[58:59], v[58:59], v[6:7] op_sel_hi:[1,0]
	v_pk_fma_f32 v[68:69], v[68:69], v[0:1], v[70:71] op_sel_hi:[1,0,1] neg_lo:[0,0,1] neg_hi:[0,0,1]
	v_pk_mul_f32 v[56:57], v[56:57], v[6:7] op_sel_hi:[1,0]
	v_pk_mul_f32 v[70:71], v[68:69], v[68:69]
	v_pk_mul_f32 v[50:51], v[50:51], v[6:7] op_sel_hi:[1,0]
	v_pk_mul_f32 v[48:49], v[48:49], v[6:7] op_sel_hi:[1,0]
	v_pk_mul_f32 v[42:43], v[42:43], v[6:7] op_sel_hi:[1,0]
	v_pk_mul_f32 v[40:41], v[40:41], v[6:7] op_sel_hi:[1,0]
	v_pk_mul_f32 v[30:31], v[30:31], v[6:7] op_sel_hi:[1,0]
	v_pk_mul_f32 v[28:29], v[28:29], v[6:7] op_sel_hi:[1,0]
	v_pk_mul_f32 v[22:23], v[22:23], v[6:7] op_sel_hi:[1,0]
	v_pk_mul_f32 v[6:7], v[20:21], v[6:7] op_sel_hi:[1,0]
	v_pk_mul_f32 v[18:19], v[16:17], v[16:17]
	v_pk_fma_f32 v[62:63], v[62:63], v[0:1], v[66:67] op_sel_hi:[1,0,1] neg_lo:[0,0,1] neg_hi:[0,0,1]
	v_pk_fma_f32 v[60:61], v[60:61], v[0:1], v[64:65] op_sel_hi:[1,0,1] neg_lo:[0,0,1] neg_hi:[0,0,1]
	v_pk_fma_f32 v[54:55], v[54:55], v[0:1], v[58:59] op_sel_hi:[1,0,1] neg_lo:[0,0,1] neg_hi:[0,0,1]
	v_pk_fma_f32 v[52:53], v[52:53], v[0:1], v[56:57] op_sel_hi:[1,0,1] neg_lo:[0,0,1] neg_hi:[0,0,1]
	v_pk_fma_f32 v[46:47], v[46:47], v[0:1], v[50:51] op_sel_hi:[1,0,1] neg_lo:[0,0,1] neg_hi:[0,0,1]
	v_pk_fma_f32 v[44:45], v[44:45], v[0:1], v[48:49] op_sel_hi:[1,0,1] neg_lo:[0,0,1] neg_hi:[0,0,1]
	v_pk_fma_f32 v[38:39], v[38:39], v[0:1], v[42:43] op_sel_hi:[1,0,1] neg_lo:[0,0,1] neg_hi:[0,0,1]
	v_pk_fma_f32 v[36:37], v[36:37], v[0:1], v[40:41] op_sel_hi:[1,0,1] neg_lo:[0,0,1] neg_hi:[0,0,1]
	v_pk_fma_f32 v[30:31], v[34:35], v[0:1], v[30:31] op_sel_hi:[1,0,1] neg_lo:[0,0,1] neg_hi:[0,0,1]
	v_pk_fma_f32 v[28:29], v[32:33], v[0:1], v[28:29] op_sel_hi:[1,0,1] neg_lo:[0,0,1] neg_hi:[0,0,1]
	v_pk_fma_f32 v[22:23], v[26:27], v[0:1], v[22:23] op_sel_hi:[1,0,1] neg_lo:[0,0,1] neg_hi:[0,0,1]
	v_pk_fma_f32 v[6:7], v[24:25], v[0:1], v[6:7] op_sel_hi:[1,0,1] neg_lo:[0,0,1] neg_hi:[0,0,1]
	v_add_f32_e32 v0, v70, v71
	v_add_f32_e32 v0, v18, v0
	v_pk_mul_f32 v[64:65], v[60:61], v[60:61]
	v_add_f32_e32 v0, v19, v0
	v_add_f32_e32 v0, v64, v0
	v_pk_mul_f32 v[66:67], v[62:63], v[62:63]
	v_add_f32_e32 v0, v65, v0
	v_add_f32_e32 v0, v66, v0
	v_pk_mul_f32 v[56:57], v[52:53], v[52:53]
	v_add_f32_e32 v0, v67, v0
	v_add_f32_e32 v0, v56, v0
	v_pk_mul_f32 v[58:59], v[54:55], v[54:55]
	v_add_f32_e32 v0, v57, v0
	v_add_f32_e32 v0, v58, v0
	v_pk_mul_f32 v[48:49], v[44:45], v[44:45]
	v_add_f32_e32 v0, v59, v0
	v_add_f32_e32 v0, v48, v0
	v_pk_mul_f32 v[50:51], v[46:47], v[46:47]
	v_add_f32_e32 v0, v49, v0
	v_add_f32_e32 v0, v50, v0
	v_pk_mul_f32 v[40:41], v[36:37], v[36:37]
	v_add_f32_e32 v0, v51, v0
	v_add_f32_e32 v0, v40, v0
	v_pk_mul_f32 v[42:43], v[38:39], v[38:39]
	v_add_f32_e32 v0, v41, v0
	v_add_f32_e32 v0, v42, v0
	v_pk_mul_f32 v[32:33], v[28:29], v[28:29]
	v_add_f32_e32 v0, v43, v0
	v_add_f32_e32 v0, v32, v0
	v_pk_mul_f32 v[34:35], v[30:31], v[30:31]
	v_add_f32_e32 v0, v33, v0
	v_add_f32_e32 v0, v34, v0
	v_pk_mul_f32 v[20:21], v[6:7], v[6:7]
	v_add_f32_e32 v0, v35, v0
	v_add_f32_e32 v0, v20, v0
	v_pk_mul_f32 v[26:27], v[22:23], v[22:23]
	v_add_f32_e32 v0, v21, v0
	v_add_f32_e32 v0, v26, v0
	v_pk_mul_f32 v[10:11], v[8:9], v[8:9]
	v_add_f32_e32 v0, v27, v0
	v_add_f32_e32 v0, v10, v0
	v_pk_mul_f32 v[14:15], v[12:13], v[12:13]
	v_add_f32_e32 v0, v11, v0
	v_add_f32_e32 v0, v14, v0
	v_add_f32_e32 v0, v15, v0
	ds_bpermute_b32 v10, v146, v0
	v_readlane_b32 s37, v255, 3
	v_readlane_b32 s36, v255, 18
	v_readlane_b32 s37, v255, 19
	v_readlane_b32 s38, v255, 4
	s_waitcnt lgkmcnt(0)
	v_add_f32_e32 v0, v0, v10
	ds_bpermute_b32 v14, v147, v0
	v_lshl_add_u64 v[10:11], s[26:27], 0, v[110:111]
	v_lshl_add_u64 v[10:11], s[76:77], 1, v[10:11]
	v_readlane_b32 s39, v255, 5
	v_readlane_b32 s40, v255, 6
	s_waitcnt lgkmcnt(0)
	v_add_f32_e32 v0, v0, v14
	v_fmamk_f32 v0, v0, 0x3c000000, v142
	v_mul_f32_e32 v14, 0x4b800000, v0
	v_cmp_gt_f32_e32 vcc, s71, v0
	v_readlane_b32 s41, v255, 7
	v_readlane_b32 s42, v255, 8
	v_cndmask_b32_e32 v0, v0, v14, vcc
	v_rsq_f32_e32 v14, v0
	v_lshlrev_b32_e32 v0, 4, v145
	v_lshl_add_u64 v[10:11], v[10:11], 0, v[0:1]
	v_readlane_b32 s43, v255, 9
	v_mul_f32_e32 v0, 0x45800000, v14
	v_cndmask_b32_e32 v0, v14, v0, vcc
	v_mul_f32_e32 v0, 0x3f24fd5c, v0
	v_readlane_b32 s44, v255, 10
	v_readlane_b32 s45, v255, 11
	v_readlane_b32 s46, v255, 12
	v_readlane_b32 s47, v255, 13
	v_readlane_b32 s48, v255, 14
	v_readlane_b32 s49, v255, 15
	s_waitcnt vmcnt(0)
	v_pk_mul_f32 v[14:15], v[68:69], v[0:1] op_sel_hi:[1,0]
	v_pk_mul_f32 v[16:17], v[16:17], v[0:1] op_sel_hi:[1,0]
	v_pk_mul_f32 v[14:15], v[14:15], v[182:183]
	v_pk_mul_f32 v[16:17], v[16:17], v[184:185]
	v_cvt_pk_bf16_f32 v92, v14, v15
	v_cvt_pk_bf16_f32 v93, v16, v17
	v_pk_mul_f32 v[14:15], v[60:61], v[0:1] op_sel_hi:[1,0]
	v_pk_mul_f32 v[16:17], v[62:63], v[0:1] op_sel_hi:[1,0]
	v_pk_mul_f32 v[14:15], v[14:15], v[186:187]
	v_pk_mul_f32 v[16:17], v[16:17], v[188:189]
	v_cvt_pk_bf16_f32 v94, v14, v15
	v_cvt_pk_bf16_f32 v95, v16, v17
	s_nop 1
	v_permlane32_swap_b32_e32 v92, v94
	v_permlane32_swap_b32_e32 v93, v95
	s_nop 0
	v_permlane16_swap_b32_e32 v92, v94
	v_permlane16_swap_b32_e32 v93, v95
	global_store_dwordx4 v[10:11], v[92:95], off
	v_pk_mul_f32 v[14:15], v[52:53], v[0:1] op_sel_hi:[1,0]
	v_pk_mul_f32 v[16:17], v[54:55], v[0:1] op_sel_hi:[1,0]
	v_pk_mul_f32 v[14:15], v[14:15], v[190:191]
	v_pk_mul_f32 v[16:17], v[16:17], v[192:193]
	v_cvt_pk_bf16_f32 v96, v14, v15
	v_cvt_pk_bf16_f32 v97, v16, v17
	v_pk_mul_f32 v[14:15], v[44:45], v[0:1] op_sel_hi:[1,0]
	v_pk_mul_f32 v[16:17], v[46:47], v[0:1] op_sel_hi:[1,0]
	v_pk_mul_f32 v[14:15], v[14:15], v[194:195]
	v_pk_mul_f32 v[16:17], v[16:17], v[196:197]
	v_cvt_pk_bf16_f32 v98, v14, v15
	v_cvt_pk_bf16_f32 v99, v16, v17
	s_nop 1
	v_permlane32_swap_b32_e32 v96, v98
	v_permlane32_swap_b32_e32 v97, v99
	s_nop 0
	v_permlane16_swap_b32_e32 v96, v98
	v_permlane16_swap_b32_e32 v97, v99
	global_store_dwordx4 v[10:11], v[96:99], off offset:64
	v_pk_mul_f32 v[14:15], v[36:37], v[0:1] op_sel_hi:[1,0]
	v_pk_mul_f32 v[16:17], v[38:39], v[0:1] op_sel_hi:[1,0]
	v_pk_mul_f32 v[14:15], v[14:15], v[198:199]
	v_pk_mul_f32 v[16:17], v[16:17], v[200:201]
	v_cvt_pk_bf16_f32 v100, v14, v15
	v_cvt_pk_bf16_f32 v101, v16, v17
	v_pk_mul_f32 v[14:15], v[28:29], v[0:1] op_sel_hi:[1,0]
	v_pk_mul_f32 v[16:17], v[30:31], v[0:1] op_sel_hi:[1,0]
	v_pk_mul_f32 v[14:15], v[14:15], v[202:203]
	v_pk_mul_f32 v[16:17], v[16:17], v[204:205]
	v_cvt_pk_bf16_f32 v102, v14, v15
	v_cvt_pk_bf16_f32 v103, v16, v17
	s_nop 1
	v_permlane32_swap_b32_e32 v100, v102
	v_permlane32_swap_b32_e32 v101, v103
	s_nop 0
	v_permlane16_swap_b32_e32 v100, v102
	v_permlane16_swap_b32_e32 v101, v103
	global_store_dwordx4 v[10:11], v[100:103], off offset:128
	v_pk_mul_f32 v[14:15], v[6:7], v[0:1] op_sel_hi:[1,0]
	v_pk_mul_f32 v[16:17], v[22:23], v[0:1] op_sel_hi:[1,0]
	v_pk_mul_f32 v[14:15], v[14:15], v[206:207]
	v_pk_mul_f32 v[16:17], v[16:17], v[208:209]
	v_cvt_pk_bf16_f32 v104, v14, v15
	v_cvt_pk_bf16_f32 v105, v16, v17
	v_pk_mul_f32 v[14:15], v[8:9], v[0:1] op_sel_hi:[1,0]
	v_pk_mul_f32 v[16:17], v[12:13], v[0:1] op_sel_hi:[1,0]
	v_pk_mul_f32 v[14:15], v[14:15], v[210:211]
	v_pk_mul_f32 v[16:17], v[16:17], v[212:213]
	v_cvt_pk_bf16_f32 v106, v14, v15
	v_cvt_pk_bf16_f32 v107, v16, v17
	s_nop 1
	v_permlane32_swap_b32_e32 v104, v106
	v_permlane32_swap_b32_e32 v105, v107
	s_nop 0
	v_permlane16_swap_b32_e32 v104, v106
	v_permlane16_swap_b32_e32 v105, v107
	global_store_dwordx4 v[10:11], v[104:107], off offset:192
	s_branch .LBB0_1582
